# GDN scan inner loop moved to f32 MFMA (v_mfma_f32_16x16x4_f32), 4 waves x 16-col tiles, state in accumulators
# speedup vs baseline: 1.0261x; 1.0261x over previous
.LBB0_533:
	s_cmpk_gt_i32 s71, 0x7f
	s_mov_b64 s[0:1], -1
	s_cbranch_scc0 .LBB0_560
	s_add_i32 s3, s71, 0xffffff80
	v_mov_b32_e32 v1, v180
	s_lshl_b32 s0, s3, 8
	s_bfe_u32 s6, s71, 0x20001
	s_and_b32 s16, s0, 0x7800
	s_waitcnt vmcnt(2)
	v_ashrrev_i32_e32 v18, 3, v1
	s_lshl_b32 s72, s6, 2
	s_lshl_b32 s0, s6, 8
	v_add_u32_e32 v21, s16, v18
	v_mov_b64_e32 v[18:19], s[22:23]
	s_mov_b32 s1, s73
	s_add_u32 s8, s22, s0
	v_mad_i64_i32 v[18:19], s[4:5], v21, s83, v[18:19]
	s_addc_u32 s9, s23, 0
	v_lshl_add_u64 v[18:19], v[18:19], 0, s[0:1]
	s_lshl_b32 s0, s3, 6
	s_and_b32 s3, s0, 64
	v_mov_b32_e32 v2, s72
	v_lshlrev_b32_e32 v20, 4, v1
	s_lshl_b32 s0, s3, 1
	global_load_dword v24, v2, s[64:65]
	global_load_dword v124, v2, s[66:67]
	v_and_b32_e32 v25, 63, v1
	v_and_b32_e32 v2, 0xf0, v20
	v_lshl_add_u64 v[18:19], v[18:19], 0, s[0:1]
	v_and_b32_e32 v20, 0x70, v20
	v_mov_b32_e32 v21, v94
	v_mov_b32_e32 v3, v94
	v_add_u32_e32 v12, 0x200, v1
	v_lshl_add_u64 v[18:19], v[18:19], 0, v[20:21]
	v_or_b32_e32 v20, s16, v25
	v_lshl_add_u64 v[10:11], s[8:9], 0, v[2:3]
	v_ashrrev_i32_e32 v2, 4, v1
	v_ashrrev_i32_e32 v12, 4, v12
	v_mul_u32_u24_e32 v20, 0x88, v20
	v_add_u32_e32 v2, s16, v2
	v_add_u32_e32 v12, s16, v12
	v_lshlrev_b32_e32 v20, 2, v20
	v_mad_i64_i32 v[6:7], s[4:5], v2, s83, v[10:11]
	v_mad_i64_i32 v[14:15], s[4:5], v12, s83, v[10:11]
	v_lshl_add_u64 v[20:21], s[26:27], 0, v[20:21]
	global_load_dwordx4 v[2:5], v[6:7], off
	s_nop 0
	global_load_dwordx4 v[6:9], v[6:7], off offset:1024
	s_nop 0
	global_load_dwordx4 v[10:13], v[14:15], off
	s_nop 0
	global_load_dwordx4 v[14:17], v[14:15], off offset:1024
	v_lshl_add_u64 v[22:23], v[20:21], 0, s[72:73]
	global_load_dwordx4 v[18:21], v[18:19], off offset:2048
	s_nop 0
	global_load_dword v126, v[22:23], off offset:512
	global_load_dword v127, v[22:23], off offset:528
	s_lshl_b32 s1, s6, 9
	v_lshlrev_b32_e32 v22, 3, v1
	s_add_u32 s1, s75, s1
	v_and_b32_e32 v22, 0xfffffe00, v22
	v_lshlrev_b32_e32 v23, 2, v25
	s_addc_u32 s4, s79, 0
	s_lshl_b32 s3, s3, 2
	v_add3_u32 v22, s82, v22, v23
	s_add_u32 s10, s1, s3
	ds_write2st64_b32 v22, v94, v94 offset1:1
	s_addc_u32 s11, s4, 0
	s_add_u32 s12, s8, s0
	s_addc_u32 s13, s9, 0
	v_mov_b32_e32 v95, v94
	s_add_u32 s14, s26, s72
	s_mov_b32 s17, 0
	v_mov_b64_e32 v[96:97], v[94:95]
	v_mov_b64_e32 v[98:99], v[94:95]
	v_mov_b64_e32 v[100:101], v[94:95]
	s_addc_u32 s15, s27, 0
	v_mov_b64_e32 v[102:103], v[94:95]
	v_mov_b64_e32 v[104:105], v[94:95]
	v_mov_b64_e32 v[106:107], v[94:95]
	v_mov_b64_e32 v[108:109], v[94:95]
	v_mov_b64_e32 v[110:111], v[94:95]
	s_waitcnt vmcnt(8)
	v_mul_f32_e32 v22, 0x3fb8aa3b, v24
	v_exp_f32_e32 v125, v22
	v_mov_b32_e32 v184, 0
	v_mov_b32_e32 v185, 0
	v_mov_b32_e32 v186, 0
	v_mov_b32_e32 v187, 0
	v_mov_b32_e32 v188, 0
	v_mov_b32_e32 v189, 0
	v_mov_b32_e32 v190, 0
	v_mov_b32_e32 v191, 0
	v_mov_b32_e32 v192, 0
	v_mov_b32_e32 v193, 0
	v_mov_b32_e32 v194, 0
	v_mov_b32_e32 v195, 0
	v_mov_b32_e32 v196, 0
	v_mov_b32_e32 v197, 0
	v_mov_b32_e32 v198, 0
	v_mov_b32_e32 v199, 0
	v_mov_b32_e32 v200, 0
	v_mov_b32_e32 v201, 0
	v_mov_b32_e32 v202, 0
	v_mov_b32_e32 v203, 0
	v_mov_b32_e32 v204, 0
	v_mov_b32_e32 v205, 0
	v_mov_b32_e32 v206, 0
	v_mov_b32_e32 v207, 0
	v_mov_b32_e32 v208, 0
	v_mov_b32_e32 v209, 0
	v_mov_b32_e32 v210, 0
	v_mov_b32_e32 v211, 0
	v_mov_b32_e32 v212, 0
	v_mov_b32_e32 v213, 0
	v_mov_b32_e32 v214, 0
	v_mov_b32_e32 v215, 0
	s_branch .LBB0_537

.LBB0_549:
	v_readfirstlane_b32 s0, v180
	s_nop 1
	s_cmpk_ge_u32 s0, 0x100
	s_cbranch_scc1 .Lgdn_done
	v_and_b32_e32 v166, 15, v180
	v_bfe_u32 v167, v180, 4, 2
	v_lshrrev_b32_e32 v168, 6, v180
	v_and_b32_e32 v177, 3, v166
	v_mul_u32_u24_e32 v177, 0x210, v177
	v_and_b32_e32 v178, 4, v166
	v_sub_u32_e32 v178, 4, v178
	v_mul_u32_u24_e32 v178, 0x2100, v178
	v_lshl_add_u32 v169, v167, 4, v177
	v_add_u32_e32 v169, v169, v178
	v_mul_u32_u24_e32 v177, 0x210, v167
	v_lshl_add_u32 v170, v166, 2, v177
	v_add_u32_e32 v170, 0x8400, v170
	v_lshlrev_b32_e32 v177, 6, v168
	v_lshl_add_u32 v177, v166, 2, v177
	v_add_u32_e32 v171, 0x10800, v177
	v_lshl_add_u32 v172, v167, 8, v177
	v_add_u32_e32 v172, 0x1d800, v172
	v_mov_b32_e32 v173, 0x14800
	v_lshlrev_b32_e32 v174, 5, v167
	v_add_u32_e32 v174, 0x14900, v174
	v_mov_b32_e32 v175, 0x21900
	v_lshl_add_u32 v176, v167, 2, v175
	v_cmp_eq_u32_e32 vcc, 1, v167
	v_cmp_eq_u32_e64 s[4:5], 2, v167
	v_cmp_eq_u32_e64 s[6:7], 3, v167
	ds_read_b128 v[22:25], v169 offset:0
	ds_read_b128 v[26:29], v169 offset:64
	ds_read_b128 v[30:33], v169 offset:128
	ds_read_b128 v[34:37], v169 offset:192
	ds_read_b128 v[38:41], v169 offset:256
	ds_read_b128 v[42:45], v169 offset:320
	ds_read_b128 v[46:49], v169 offset:384
	ds_read_b128 v[50:53], v169 offset:448
	ds_read_b32 v54, v170 offset:0
	ds_read_b32 v55, v170 offset:64
	ds_read_b32 v56, v170 offset:128
	ds_read_b32 v57, v170 offset:192
	ds_read_b32 v58, v170 offset:256
	ds_read_b32 v59, v170 offset:320
	ds_read_b32 v60, v170 offset:384
	ds_read_b32 v61, v170 offset:448
	ds_read_b32 v70, v171 offset:0
	ds_read_b32 v71, v171 offset:256
	ds_read_b32 v72, v171 offset:512
	ds_read_b32 v73, v171 offset:768
	ds_read_b128 v[132:135], v175 offset:0
	ds_read_b128 v[136:139], v175 offset:256
	ds_read_b32 v151, v176 offset:256
	ds_read_b32 v152, v176 offset:512
	ds_read_b32 v150, v173 offset:32
	ds_read_b64 v[148:149], v173 offset:64
	ds_read_b128 v[140:143], v173 offset:96
	ds_read_b128 v[144:147], v174 offset:0
	s_mov_b32 s1, 0
.Lgdn_loop:
	s_waitcnt lgkmcnt(0)
	v_mfma_f32_16x16x4_f32 v[96:99], v22, v184, 0
	v_mfma_f32_16x16x4_f32 v[100:103], v23, v185, 0
	v_mfma_f32_16x16x4_f32 v[96:99], v24, v186, v[96:99]
	v_mfma_f32_16x16x4_f32 v[100:103], v25, v187, v[100:103]
	v_pk_mul_f32 v[184:185], v[184:185], v[138:139] op_sel:[0,1] op_sel_hi:[1,1]
	v_pk_mul_f32 v[186:187], v[186:187], v[138:139] op_sel:[0,1] op_sel_hi:[1,1]
	v_mfma_f32_16x16x4_f32 v[96:99], v26, v188, v[96:99]
	v_mfma_f32_16x16x4_f32 v[100:103], v27, v189, v[100:103]
	v_mfma_f32_16x16x4_f32 v[96:99], v28, v190, v[96:99]
	v_mfma_f32_16x16x4_f32 v[100:103], v29, v191, v[100:103]
	v_pk_mul_f32 v[188:189], v[188:189], v[138:139] op_sel:[0,1] op_sel_hi:[1,1]
	v_pk_mul_f32 v[190:191], v[190:191], v[138:139] op_sel:[0,1] op_sel_hi:[1,1]
	v_mfma_f32_16x16x4_f32 v[96:99], v30, v192, v[96:99]
	v_mfma_f32_16x16x4_f32 v[100:103], v31, v193, v[100:103]
	v_mfma_f32_16x16x4_f32 v[96:99], v32, v194, v[96:99]
	v_mfma_f32_16x16x4_f32 v[100:103], v33, v195, v[100:103]
	v_pk_mul_f32 v[192:193], v[192:193], v[138:139] op_sel:[0,1] op_sel_hi:[1,1]
	v_pk_mul_f32 v[194:195], v[194:195], v[138:139] op_sel:[0,1] op_sel_hi:[1,1]
	v_mfma_f32_16x16x4_f32 v[96:99], v34, v196, v[96:99]
	v_mfma_f32_16x16x4_f32 v[100:103], v35, v197, v[100:103]
	v_mfma_f32_16x16x4_f32 v[96:99], v36, v198, v[96:99]
	v_mfma_f32_16x16x4_f32 v[100:103], v37, v199, v[100:103]
	v_pk_mul_f32 v[196:197], v[196:197], v[138:139] op_sel:[0,1] op_sel_hi:[1,1]
	v_pk_mul_f32 v[198:199], v[198:199], v[138:139] op_sel:[0,1] op_sel_hi:[1,1]
	v_mfma_f32_16x16x4_f32 v[96:99], v38, v200, v[96:99]
	v_mfma_f32_16x16x4_f32 v[100:103], v39, v201, v[100:103]
	v_mfma_f32_16x16x4_f32 v[96:99], v40, v202, v[96:99]
	v_mfma_f32_16x16x4_f32 v[100:103], v41, v203, v[100:103]
	v_pk_mul_f32 v[200:201], v[200:201], v[138:139] op_sel:[0,1] op_sel_hi:[1,1]
	v_pk_mul_f32 v[202:203], v[202:203], v[138:139] op_sel:[0,1] op_sel_hi:[1,1]
	v_mfma_f32_16x16x4_f32 v[96:99], v42, v204, v[96:99]
	v_mfma_f32_16x16x4_f32 v[100:103], v43, v205, v[100:103]
	v_mfma_f32_16x16x4_f32 v[96:99], v44, v206, v[96:99]
	v_mfma_f32_16x16x4_f32 v[100:103], v45, v207, v[100:103]
	v_pk_mul_f32 v[204:205], v[204:205], v[138:139] op_sel:[0,1] op_sel_hi:[1,1]
	v_pk_mul_f32 v[206:207], v[206:207], v[138:139] op_sel:[0,1] op_sel_hi:[1,1]
	v_mfma_f32_16x16x4_f32 v[96:99], v46, v208, v[96:99]
	v_mfma_f32_16x16x4_f32 v[100:103], v47, v209, v[100:103]
	v_mfma_f32_16x16x4_f32 v[96:99], v48, v210, v[96:99]
	v_mfma_f32_16x16x4_f32 v[100:103], v49, v211, v[100:103]
	v_pk_mul_f32 v[208:209], v[208:209], v[138:139] op_sel:[0,1] op_sel_hi:[1,1]
	v_pk_mul_f32 v[210:211], v[210:211], v[138:139] op_sel:[0,1] op_sel_hi:[1,1]
	v_mfma_f32_16x16x4_f32 v[96:99], v50, v212, v[96:99]
	v_mfma_f32_16x16x4_f32 v[100:103], v51, v213, v[100:103]
	v_mfma_f32_16x16x4_f32 v[96:99], v52, v214, v[96:99]
	v_mfma_f32_16x16x4_f32 v[100:103], v53, v215, v[100:103]
	v_pk_mul_f32 v[212:213], v[212:213], v[138:139] op_sel:[0,1] op_sel_hi:[1,1]
	v_pk_mul_f32 v[214:215], v[214:215], v[138:139] op_sel:[0,1] op_sel_hi:[1,1]
	ds_read_b128 v[22:25], v169 offset:2112
	ds_read_b128 v[26:29], v169 offset:2176
	ds_read_b128 v[30:33], v169 offset:2240
	ds_read_b128 v[34:37], v169 offset:2304
	ds_read_b128 v[38:41], v169 offset:2368
	ds_read_b128 v[42:45], v169 offset:2432
	ds_read_b128 v[46:49], v169 offset:2496
	ds_read_b128 v[50:53], v169 offset:2560
	ds_read_b32 v62, v170 offset:2112
	ds_read_b32 v63, v170 offset:2176
	ds_read_b32 v64, v170 offset:2240
	ds_read_b32 v65, v170 offset:2304
	ds_read_b32 v66, v170 offset:2368
	ds_read_b32 v67, v170 offset:2432
	ds_read_b32 v68, v170 offset:2496
	ds_read_b32 v69, v170 offset:2560
	ds_read_b32 v74, v171 offset:1024
	ds_read_b32 v75, v171 offset:1280
	ds_read_b32 v76, v171 offset:1536
	ds_read_b32 v77, v171 offset:1792
	ds_read_b128 v[216:219], v175 offset:16
	ds_read_b128 v[220:223], v175 offset:272
	ds_read_b32 v235, v176 offset:272
	ds_read_b32 v236, v176 offset:528
	ds_read_b32 v234, v173 offset:176
	ds_read_b64 v[232:233], v173 offset:208
	ds_read_b128 v[224:227], v173 offset:240
	ds_read_b128 v[228:231], v174 offset:144
	v_pk_add_f32 v[96:97], v[96:97], v[100:101]
	v_pk_add_f32 v[98:99], v[98:99], v[102:103]
	v_mov_b32_e32 v104, v96
	v_mov_b32_e32 v105, v97
	v_mov_b32_e32 v106, v98
	v_mov_b32_e32 v107, v99
	v_permlane16_swap_b32_e32 v96, v104
	v_permlane16_swap_b32_e32 v97, v105
	v_permlane16_swap_b32_e32 v98, v106
	v_permlane16_swap_b32_e32 v99, v107
	v_fma_f32 v114, -v136, v96, v70
	v_fma_f32 v115, -v137, v97, v71
	v_fma_f32 v116, -v138, v98, v72
	v_fma_f32 v117, -v139, v99, v73
	v_mul_f32_e32 v108, v132, v114
	v_mul_f32_e32 v109, v133, v115
	v_mul_f32_e32 v110, v134, v116
	v_mul_f32_e32 v111, v135, v117
	v_fma_f32 v109, -v150, v108, v109
	v_fma_f32 v110, -v148, v108, v110
	v_fma_f32 v110, -v149, v109, v110
	v_fma_f32 v111, -v140, v108, v111
	v_fma_f32 v111, -v141, v109, v111
	v_fma_f32 v111, -v142, v110, v111
	v_cndmask_b32_e32 v183, v104, v105, vcc
	v_cndmask_b32_e64 v183, v183, v106, s[4:5]
	v_cndmask_b32_e64 v183, v183, v107, s[6:7]
	v_mul_f32_e32 v179, v151, v183
	v_fmac_f32_e32 v179, v144, v108
	v_fmac_f32_e32 v179, v145, v109
	v_fmac_f32_e32 v179, v146, v110
	v_fmac_f32_e32 v179, v147, v111
	ds_write_b32 v172, v179 offset:0
	v_cndmask_b32_e32 v182, v108, v109, vcc
	v_cndmask_b32_e64 v182, v182, v110, s[4:5]
	v_cndmask_b32_e64 v182, v182, v111, s[6:7]
	v_mul_f32_e32 v182, v152, v182
	s_nop 1
	v_mfma_f32_16x16x4_f32 v[184:187], v54, v182, v[184:187]
	v_mfma_f32_16x16x4_f32 v[188:191], v55, v182, v[188:191]
	v_mfma_f32_16x16x4_f32 v[192:195], v56, v182, v[192:195]
	v_mfma_f32_16x16x4_f32 v[196:199], v57, v182, v[196:199]
	v_mfma_f32_16x16x4_f32 v[200:203], v58, v182, v[200:203]
	v_mfma_f32_16x16x4_f32 v[204:207], v59, v182, v[204:207]
	v_mfma_f32_16x16x4_f32 v[208:211], v60, v182, v[208:211]
	v_mfma_f32_16x16x4_f32 v[212:215], v61, v182, v[212:215]
	s_nop 3
	s_waitcnt lgkmcnt(0)
	v_mfma_f32_16x16x4_f32 v[96:99], v22, v184, 0
	v_mfma_f32_16x16x4_f32 v[100:103], v23, v185, 0
	v_mfma_f32_16x16x4_f32 v[96:99], v24, v186, v[96:99]
	v_mfma_f32_16x16x4_f32 v[100:103], v25, v187, v[100:103]
	v_pk_mul_f32 v[184:185], v[184:185], v[222:223] op_sel:[0,1] op_sel_hi:[1,1]
	v_pk_mul_f32 v[186:187], v[186:187], v[222:223] op_sel:[0,1] op_sel_hi:[1,1]
	v_mfma_f32_16x16x4_f32 v[96:99], v26, v188, v[96:99]
	v_mfma_f32_16x16x4_f32 v[100:103], v27, v189, v[100:103]
	v_mfma_f32_16x16x4_f32 v[96:99], v28, v190, v[96:99]
	v_mfma_f32_16x16x4_f32 v[100:103], v29, v191, v[100:103]
	v_pk_mul_f32 v[188:189], v[188:189], v[222:223] op_sel:[0,1] op_sel_hi:[1,1]
	v_pk_mul_f32 v[190:191], v[190:191], v[222:223] op_sel:[0,1] op_sel_hi:[1,1]
	v_mfma_f32_16x16x4_f32 v[96:99], v30, v192, v[96:99]
	v_mfma_f32_16x16x4_f32 v[100:103], v31, v193, v[100:103]
	v_mfma_f32_16x16x4_f32 v[96:99], v32, v194, v[96:99]
	v_mfma_f32_16x16x4_f32 v[100:103], v33, v195, v[100:103]
	v_pk_mul_f32 v[192:193], v[192:193], v[222:223] op_sel:[0,1] op_sel_hi:[1,1]
	v_pk_mul_f32 v[194:195], v[194:195], v[222:223] op_sel:[0,1] op_sel_hi:[1,1]
	v_mfma_f32_16x16x4_f32 v[96:99], v34, v196, v[96:99]
	v_mfma_f32_16x16x4_f32 v[100:103], v35, v197, v[100:103]
	v_mfma_f32_16x16x4_f32 v[96:99], v36, v198, v[96:99]
	v_mfma_f32_16x16x4_f32 v[100:103], v37, v199, v[100:103]
	v_pk_mul_f32 v[196:197], v[196:197], v[222:223] op_sel:[0,1] op_sel_hi:[1,1]
	v_pk_mul_f32 v[198:199], v[198:199], v[222:223] op_sel:[0,1] op_sel_hi:[1,1]
	v_mfma_f32_16x16x4_f32 v[96:99], v38, v200, v[96:99]
	v_mfma_f32_16x16x4_f32 v[100:103], v39, v201, v[100:103]
	v_mfma_f32_16x16x4_f32 v[96:99], v40, v202, v[96:99]
	v_mfma_f32_16x16x4_f32 v[100:103], v41, v203, v[100:103]
	v_pk_mul_f32 v[200:201], v[200:201], v[222:223] op_sel:[0,1] op_sel_hi:[1,1]
	v_pk_mul_f32 v[202:203], v[202:203], v[222:223] op_sel:[0,1] op_sel_hi:[1,1]
	v_mfma_f32_16x16x4_f32 v[96:99], v42, v204, v[96:99]
	v_mfma_f32_16x16x4_f32 v[100:103], v43, v205, v[100:103]
	v_mfma_f32_16x16x4_f32 v[96:99], v44, v206, v[96:99]
	v_mfma_f32_16x16x4_f32 v[100:103], v45, v207, v[100:103]
	v_pk_mul_f32 v[204:205], v[204:205], v[222:223] op_sel:[0,1] op_sel_hi:[1,1]
	v_pk_mul_f32 v[206:207], v[206:207], v[222:223] op_sel:[0,1] op_sel_hi:[1,1]
	v_mfma_f32_16x16x4_f32 v[96:99], v46, v208, v[96:99]
	v_mfma_f32_16x16x4_f32 v[100:103], v47, v209, v[100:103]
	v_mfma_f32_16x16x4_f32 v[96:99], v48, v210, v[96:99]
	v_mfma_f32_16x16x4_f32 v[100:103], v49, v211, v[100:103]
	v_pk_mul_f32 v[208:209], v[208:209], v[222:223] op_sel:[0,1] op_sel_hi:[1,1]
	v_pk_mul_f32 v[210:211], v[210:211], v[222:223] op_sel:[0,1] op_sel_hi:[1,1]
	v_mfma_f32_16x16x4_f32 v[96:99], v50, v212, v[96:99]
	v_mfma_f32_16x16x4_f32 v[100:103], v51, v213, v[100:103]
	v_mfma_f32_16x16x4_f32 v[96:99], v52, v214, v[96:99]
	v_mfma_f32_16x16x4_f32 v[100:103], v53, v215, v[100:103]
	v_pk_mul_f32 v[212:213], v[212:213], v[222:223] op_sel:[0,1] op_sel_hi:[1,1]
	v_pk_mul_f32 v[214:215], v[214:215], v[222:223] op_sel:[0,1] op_sel_hi:[1,1]
	ds_read_b128 v[22:25], v169 offset:4224
	ds_read_b128 v[26:29], v169 offset:4288
	ds_read_b128 v[30:33], v169 offset:4352
	ds_read_b128 v[34:37], v169 offset:4416
	ds_read_b128 v[38:41], v169 offset:4480
	ds_read_b128 v[42:45], v169 offset:4544
	ds_read_b128 v[46:49], v169 offset:4608
	ds_read_b128 v[50:53], v169 offset:4672
	ds_read_b32 v54, v170 offset:4224
	ds_read_b32 v55, v170 offset:4288
	ds_read_b32 v56, v170 offset:4352
	ds_read_b32 v57, v170 offset:4416
	ds_read_b32 v58, v170 offset:4480
	ds_read_b32 v59, v170 offset:4544
	ds_read_b32 v60, v170 offset:4608
	ds_read_b32 v61, v170 offset:4672
	ds_read_b32 v70, v171 offset:2048
	ds_read_b32 v71, v171 offset:2304
	ds_read_b32 v72, v171 offset:2560
	ds_read_b32 v73, v171 offset:2816
	ds_read_b128 v[132:135], v175 offset:32
	ds_read_b128 v[136:139], v175 offset:288
	ds_read_b32 v151, v176 offset:288
	ds_read_b32 v152, v176 offset:544
	ds_read_b32 v150, v173 offset:544
	ds_read_b64 v[148:149], v173 offset:576
	ds_read_b128 v[140:143], v173 offset:608
	ds_read_b128 v[144:147], v174 offset:512
	v_pk_add_f32 v[96:97], v[96:97], v[100:101]
	v_pk_add_f32 v[98:99], v[98:99], v[102:103]
	v_mov_b32_e32 v104, v96
	v_mov_b32_e32 v105, v97
	v_mov_b32_e32 v106, v98
	v_mov_b32_e32 v107, v99
	v_permlane16_swap_b32_e32 v96, v104
	v_permlane16_swap_b32_e32 v97, v105
	v_permlane16_swap_b32_e32 v98, v106
	v_permlane16_swap_b32_e32 v99, v107
	v_fma_f32 v114, -v220, v96, v74
	v_fma_f32 v115, -v221, v97, v75
	v_fma_f32 v116, -v222, v98, v76
	v_fma_f32 v117, -v223, v99, v77
	v_mul_f32_e32 v108, v216, v114
	v_mul_f32_e32 v109, v217, v115
	v_mul_f32_e32 v110, v218, v116
	v_mul_f32_e32 v111, v219, v117
	v_fma_f32 v109, -v234, v108, v109
	v_fma_f32 v110, -v232, v108, v110
	v_fma_f32 v110, -v233, v109, v110
	v_fma_f32 v111, -v224, v108, v111
	v_fma_f32 v111, -v225, v109, v111
	v_fma_f32 v111, -v226, v110, v111
	v_cndmask_b32_e32 v183, v104, v105, vcc
	v_cndmask_b32_e64 v183, v183, v106, s[4:5]
	v_cndmask_b32_e64 v183, v183, v107, s[6:7]
	v_mul_f32_e32 v179, v235, v183
	v_fmac_f32_e32 v179, v228, v108
	v_fmac_f32_e32 v179, v229, v109
	v_fmac_f32_e32 v179, v230, v110
	v_fmac_f32_e32 v179, v231, v111
	ds_write_b32 v172, v179 offset:1024
	v_cndmask_b32_e32 v182, v108, v109, vcc
	v_cndmask_b32_e64 v182, v182, v110, s[4:5]
	v_cndmask_b32_e64 v182, v182, v111, s[6:7]
	v_mul_f32_e32 v182, v236, v182
	s_nop 1
	v_mfma_f32_16x16x4_f32 v[184:187], v62, v182, v[184:187]
	v_mfma_f32_16x16x4_f32 v[188:191], v63, v182, v[188:191]
	v_mfma_f32_16x16x4_f32 v[192:195], v64, v182, v[192:195]
	v_mfma_f32_16x16x4_f32 v[196:199], v65, v182, v[196:199]
	v_mfma_f32_16x16x4_f32 v[200:203], v66, v182, v[200:203]
	v_mfma_f32_16x16x4_f32 v[204:207], v67, v182, v[204:207]
	v_mfma_f32_16x16x4_f32 v[208:211], v68, v182, v[208:211]
	v_mfma_f32_16x16x4_f32 v[212:215], v69, v182, v[212:215]
	s_nop 3
	v_add_u32_e32 v169, 0x1080, v169
	v_add_u32_e32 v170, 0x1080, v170
	v_add_u32_e32 v171, 0x800, v171
	v_add_u32_e32 v172, 0x800, v172
	v_add_u32_e32 v173, 0x200, v173
	v_add_u32_e32 v174, 0x200, v174
	v_add_u32_e32 v175, 0x20, v175
	v_add_u32_e32 v176, 0x20, v176
	s_add_i32 s1, s1, 1
	s_cmp_lg_u32 s1, 8
	s_cbranch_scc1 .Lgdn_loop
.Lgdn_done:
	v_cmp_gt_i32_e32 vcc, s88, v112
	s_waitcnt lgkmcnt(0)
	s_barrier
	s_and_saveexec_b64 s[0:1], vcc
	s_xor_b64 s[0:1], exec, s[0:1]
	s_cbranch_execz .LBB0_536
	v_max_i32_e32 v24, 0xe00, v112
	v_sub_u32_e32 v24, v24, v112
	v_lshlrev_b32_e32 v22, 2, v128
	v_mov_b32_e32 v23, v94
	v_add_u32_e32 v24, 0x1ff, v24
	s_movk_i32 s3, 0x1ff
	v_lshl_add_u64 v[22:23], s[10:11], 0, v[22:23]
	v_cmp_lt_u32_e32 vcc, s3, v24
	s_mov_b64 s[6:7], -1
	s_and_saveexec_b64 s[4:5], vcc
	s_cbranch_execz .LBB0_556
	v_lshrrev_b32_e32 v24, 9, v24
	v_add_u32_e32 v26, 1, v24
	v_and_b32_e32 v27, 0xfffffe, v26
	s_mov_b32 s6, s72
	s_mov_b32 s7, s73
	v_lshl_add_u32 v28, v112, 2, s89
	s_mov_b64 s[80:81], 0
	v_mov_b32_e32 v29, v27
	v_mov_b64_e32 v[24:25], v[112:113]
